# attention QK blocks: counted lgkmcnt per K fragment instead of one full LDS drain before the first MFMA
# speedup vs baseline: 1.0001x; 1.0001x over previous
.LBB0_741:
	s_cmp_lt_u32 s43, 2
	s_cselect_b32 s3, s94, 0xffffff00
	s_add_i32 s3, s3, s2
	s_cmp_ge_i32 s50, s3
	s_cselect_b64 s[36:37], -1, 0
	s_cmp_lt_i32 s50, s3
	s_cselect_b64 s[38:39], -1, 0
	s_or_b32 s2, s3, 33
	s_cmp_le_i32 s2, s48
	s_cselect_b64 s[40:41], -1, 0
	s_cmp_gt_i32 s2, s48
	s_cselect_b64 s[52:53], -1, 0
	s_and_b64 s[38:39], s[38:39], s[52:53]
	s_and_b64 vcc, exec, s[38:39]
	s_cbranch_vccnz .LBB0_786
	s_mul_hi_u32 s2, s43, 0xaaaaaaab
	s_lshr_b32 s2, s2, 1
	s_mul_i32 s2, s2, 3
	s_sub_i32 s2, s43, s2
	s_lshl_b32 s2, s2, 15
	s_add_i32 s2, s2, 0
	v_cndmask_b32_e64 v0, 0, 1, s[36:37]
	v_cmp_ne_u32_e64 s[38:39], 1, v0
	s_andn2_b64 vcc, exec, s[36:37]
	v_add_u32_e32 v4, s2, v192
	v_add_u32_e32 v3, s2, v193
	v_add_u32_e32 v2, s2, v194
	v_add_u32_e32 v0, s2, v195
	s_cbranch_vccnz .LBB0_744
	ds_read_b128 v[6:9], v4
	ds_read_b128 v[10:13], v4 offset:4096
	ds_read_b128 v[18:21], v3
	ds_read_b128 v[22:25], v3 offset:4096
	ds_read_b128 v[26:29], v2
	ds_read_b128 v[64:67], v2 offset:4096
	ds_read_b128 v[68:71], v0
	ds_read_b128 v[72:75], v0 offset:4096
	s_setprio 1
	s_waitcnt lgkmcnt(7)
	v_mfma_f32_32x32x16_bf16 v[112:127], v[6:9], v[160:163], 0
	s_waitcnt lgkmcnt(6)
	v_mfma_f32_32x32x16_bf16 v[96:111], v[10:13], v[160:163], 0
	s_waitcnt lgkmcnt(5)
	v_mfma_f32_32x32x16_bf16 v[112:127], v[18:21], v[164:167], v[112:127]
	s_waitcnt lgkmcnt(4)
	v_mfma_f32_32x32x16_bf16 v[96:111], v[22:25], v[164:167], v[96:111]
	s_waitcnt lgkmcnt(3)
	v_mfma_f32_32x32x16_bf16 v[112:127], v[26:29], v[168:171], v[112:127]
	s_waitcnt lgkmcnt(2)
	v_mfma_f32_32x32x16_bf16 v[96:111], v[64:67], v[168:171], v[96:111]
	s_waitcnt lgkmcnt(1)
	v_mfma_f32_32x32x16_bf16 v[112:127], v[68:71], v[172:175], v[112:127]
	s_waitcnt lgkmcnt(0)
	v_mfma_f32_32x32x16_bf16 v[96:111], v[72:75], v[172:175], v[96:111]
	s_setprio 0
	s_branch .LBB0_745

.LBB0_745:
	v_cndmask_b32_e64 v5, 0, 1, s[40:41]
	v_cmp_ne_u32_e64 s[36:37], 1, v5
	s_andn2_b64 vcc, exec, s[40:41]
	s_cbranch_vccnz .LBB0_747
	ds_read_b128 v[6:9], v4 offset:8192
	ds_read_b128 v[10:13], v4 offset:12288
	ds_read_b128 v[18:21], v3 offset:8192
	ds_read_b128 v[22:25], v3 offset:12288
	ds_read_b128 v[26:29], v2 offset:8192
	ds_read_b128 v[2:5], v2 offset:12288
	ds_read_b128 v[128:131], v0 offset:8192
	ds_read_b128 v[132:135], v0 offset:12288
	s_setprio 1
	s_waitcnt lgkmcnt(7)
	v_mfma_f32_32x32x16_bf16 v[80:95], v[6:9], v[160:163], 0
	s_waitcnt lgkmcnt(6)
	v_mfma_f32_32x32x16_bf16 v[64:79], v[10:13], v[160:163], 0
	s_waitcnt lgkmcnt(5)
	v_mfma_f32_32x32x16_bf16 v[80:95], v[18:21], v[164:167], v[80:95]
	s_waitcnt lgkmcnt(4)
	v_mfma_f32_32x32x16_bf16 v[64:79], v[22:25], v[164:167], v[64:79]
	s_waitcnt lgkmcnt(3)
	v_mfma_f32_32x32x16_bf16 v[80:95], v[26:29], v[168:171], v[80:95]
	s_waitcnt lgkmcnt(2)
	v_mfma_f32_32x32x16_bf16 v[64:79], v[2:5], v[168:171], v[64:79]
	s_waitcnt lgkmcnt(1)
	v_mfma_f32_32x32x16_bf16 v[80:95], v[128:131], v[172:175], v[80:95]
	s_waitcnt lgkmcnt(0)
	v_mfma_f32_32x32x16_bf16 v[64:79], v[132:135], v[172:175], v[64:79]
	s_setprio 0
	s_and_b64 vcc, exec, s[38:39]
	s_cbranch_vccz .LBB0_748
	s_branch .LBB0_757

.Lk0_qk0:
	ds_read_b128 v[66:69], v135
	ds_read_b128 v[70:73], v135 offset:4096
	ds_read_b128 v[74:77], v134
	ds_read_b128 v[78:81], v134 offset:4096
	ds_read_b128 v[82:85], v133
	ds_read_b128 v[86:89], v133 offset:4096
	ds_read_b128 v[90:93], v132
	ds_read_b128 v[136:139], v132 offset:4096
	s_setprio 1
	s_waitcnt lgkmcnt(7)
	v_mfma_f32_32x32x16_bf16 v[112:127], v[66:69], v[2:5], 0
	s_waitcnt lgkmcnt(6)
	v_mfma_f32_32x32x16_bf16 v[96:111], v[70:73], v[2:5], 0
	s_waitcnt lgkmcnt(5)
	v_mfma_f32_32x32x16_bf16 v[112:127], v[74:77], v[6:9], v[112:127]
	s_waitcnt lgkmcnt(4)
	v_mfma_f32_32x32x16_bf16 v[96:111], v[78:81], v[6:9], v[96:111]
	s_waitcnt lgkmcnt(3)
	v_mfma_f32_32x32x16_bf16 v[112:127], v[82:85], v[10:13], v[112:127]
	s_waitcnt lgkmcnt(2)
	v_mfma_f32_32x32x16_bf16 v[96:111], v[86:89], v[10:13], v[96:111]
	s_waitcnt lgkmcnt(1)
	v_mfma_f32_32x32x16_bf16 v[112:127], v[90:93], v[18:21], v[112:127]
	s_waitcnt lgkmcnt(0)
	v_mfma_f32_32x32x16_bf16 v[96:111], v[136:139], v[18:21], v[96:111]
	s_setprio 0

.Lk0_qk1:
	ds_read_b128 v[64:67], v135 offset:8192
	ds_read_b128 v[80:83], v135 offset:12288
	ds_read_b128 v[136:139], v134 offset:8192
	ds_read_b128 v[140:143], v134 offset:12288
	ds_read_b128 v[144:147], v133 offset:8192
	ds_read_b128 v[148:151], v133 offset:12288
	ds_read_b128 v[152:155], v132 offset:8192
	ds_read_b128 v[132:135], v132 offset:12288
	s_setprio 1
	s_waitcnt lgkmcnt(7)
	v_mfma_f32_32x32x16_bf16 v[64:79], v[64:67], v[2:5], 0
	s_waitcnt lgkmcnt(6)
	v_mfma_f32_32x32x16_bf16 v[80:95], v[80:83], v[2:5], 0
	s_waitcnt lgkmcnt(5)
	v_mfma_f32_32x32x16_bf16 v[64:79], v[136:139], v[6:9], v[64:79]
	s_waitcnt lgkmcnt(4)
	v_mfma_f32_32x32x16_bf16 v[80:95], v[140:143], v[6:9], v[80:95]
	s_waitcnt lgkmcnt(3)
	v_mfma_f32_32x32x16_bf16 v[64:79], v[144:147], v[10:13], v[64:79]
	s_waitcnt lgkmcnt(2)
	v_mfma_f32_32x32x16_bf16 v[80:95], v[148:151], v[10:13], v[80:95]
	s_waitcnt lgkmcnt(1)
	v_mfma_f32_32x32x16_bf16 v[64:79], v[152:155], v[18:21], v[64:79]
	s_waitcnt lgkmcnt(0)
	v_mfma_f32_32x32x16_bf16 v[80:95], v[132:135], v[18:21], v[80:95]
	s_setprio 0
